# baseline (speedup 1.0000x reference)
; __device__ __forceinline__ float row_rs(const float* RSS, int grow) { return __builtin_amdgcn_rsqf(RSS[grow] * (1.0f / 1024.0f) + EPS); }
; __device__ __forceinline__ f32x2 vstat(const float* VS, const float* RSS, int grow) { const float rs = row_rs(RSS, grow); const float mean = VS[2 * grow] * (1.0f / 1024.0f); const float var = fmaxf(VS[2 * grow + 1] * (1.0f / 1024.0f) - mean * mean, 0.f); return (f32x2){mean, rs * __builtin_amdgcn_rsqf(rs * rs * var + EPS)}; }
; __device__ __forceinline__ void mixer_phase(const Args& a, LAS unsigned char* lds, int l, int pass, int tid, int lane, int wave) {
;     ...
;             int tl = tid; asm volatile("" : "+v"(tl)); const int lane = tl & 63;
;             const int q = tl >> 4, o = tl & 15, wt = w >> 1, wc2 = w & 1, fr = lane & 15, fq = lane >> 4;
;             constexpr size_t HSTR = (size_t)32768 * 384;
;             const bf16* Hu = PROJ + (size_t)(unit * 128) * 384;
;             const bf16* vsrc = Hu + (size_t)(4 * q) * 384 + 128 + 8 * o;
;             f32x2 st[4];
; #pragma unroll
;             for (int i = 0; i < 4; ++i) st[i] = vstat(VS, RSS, grow0 + 4 * q + i);
;             float ssb[2] = {0.f, 0.f};
;             v4u vr[4];
; #pragma unroll
;             for (int i = 0; i < 4; ++i) vr[i] = *(const v4u*)(vsrc + (size_t)i * 384);
;             const bf16* wm0 = WM + ((size_t)(l * 8 * 2) * 128 + 32 * wt + fr) * 128 + 8 * fq;
;             const int t0 = 32 * wt + fr, cbw = 64 * wc2 + 8 * fq;
;             const float rsr[2] = {row_rs(RSS, grow0 + t0), row_rs(RSS, grow0 + t0 + 16)};
;             UZ uz[2];
; #pragma unroll
;             for (int m = 0; m < 2; ++m) uz[m] = load_uz_hm(Hu + (size_t)(t0 + 16 * m) * 384, sgb + t0 + 16 * m, cbw);
.LBB0_174:
	v_mov_b32_e32 v48, v122
	s_lshl_b32 s6, s17, 7
	s_add_i32 s79, s6, s0
	v_ashrrev_i32_e32 v49, 4, v48
	v_lshlrev_b32_e32 v50, 2, v49
	v_add_u32_e32 v2, s79, v50
	v_ashrrev_i32_e32 v3, 31, v2
	v_lshl_add_u64 v[4:5], v[2:3], 2, s[68:69]
	v_lshlrev_b32_e32 v2, 1, v2
	global_load_dwordx4 v[18:21], v[4:5], off
	v_ashrrev_i32_e32 v3, 31, v2
	v_lshl_add_u64 v[4:5], v[2:3], 2, s[66:67]
	global_load_dwordx3 v[22:24], v[4:5], off
	v_or_b32_e32 v4, 2, v2
	v_or_b32_e32 v6, 4, v2
	v_or_b32_e32 v2, 6, v2
	v_ashrrev_i32_e32 v7, 31, v6
	v_ashrrev_i32_e32 v3, 31, v2
	v_ashrrev_i32_e32 v5, 31, v4
	v_lshl_add_u64 v[6:7], v[6:7], 2, s[66:67]
	v_lshl_add_u64 v[2:3], v[2:3], 2, s[66:67]
	global_load_dwordx2 v[26:27], v[6:7], off
	global_load_dwordx2 v[28:29], v[2:3], off
	v_lshl_add_u64 v[2:3], v[4:5], 2, s[66:67]
	global_load_dword v25, v[2:3], off offset:4
	v_and_b32_e32 v120, 15, v48
	v_lshlrev_b32_e32 v229, 5, v120
	v_add_u32_e32 v229, 0x15800, v229
	v_or_b32_e32 v42, s30, v120
	v_add_u32_e32 v2, s79, v42
	v_ashrrev_i32_e32 v3, 31, v2
	v_lshl_add_u64 v[2:3], v[2:3], 2, s[68:69]
	global_load_dword v34, v[2:3], off
	global_load_dword v35, v[2:3], off offset:64
	s_mul_i32 s7, s17, 0x18000
	s_mul_hi_i32 s44, s6, 0x300
	s_add_u32 s6, s47, s7
	v_bfe_u32 v166, v48, 4, 2
	s_addc_u32 s7, s76, s44
	s_add_u32 s6, s6, s100
	s_addc_u32 s7, s7, 0
	v_ashrrev_i32_e32 v43, 31, v42
	v_lshlrev_b32_e32 v52, 4, v166
	v_mov_b64_e32 v[30:31], s[6:7]
	v_lshl_add_u64 v[128:129], v[42:43], 2, s[70:71]
	v_or_b32_e32 v43, 16, v42
	v_mov_b32_e32 v45, v1
	v_lshlrev_b32_e32 v0, 4, v120
	v_lshl_or_b32 v44, s35, 1, v52
	v_mad_i64_i32 v[2:3], s[6:7], v50, s31, v[30:31]
	v_mad_i64_i32 v[4:5], s[6:7], v42, s31, v[30:31]
	v_lshl_add_u64 v[14:15], v[2:3], 0, v[0:1]
	v_lshl_add_u64 v[32:33], v[4:5], 0, v[44:45]
	global_load_dwordx4 v[2:5], v[14:15], off offset:256 nt
	global_load_dwordx4 v[6:9], v[14:15], off offset:1024 nt
	global_load_dwordx4 v[10:13], v[14:15], off offset:1792 nt
	s_nop 0
	global_load_dwordx4 v[14:17], v[14:15], off offset:2560 nt
	s_nop 0
	global_load_dwordx4 v[74:77], v[32:33], off nt
	v_lshlrev_b32_e32 v46, 5, v120
	v_mov_b32_e32 v47, v1
	v_lshl_add_u64 v[130:131], s[8:9], 0, v[46:47]
	v_lshl_add_u64 v[132:133], s[10:11], 0, v[46:47]
	v_lshlrev_b32_e32 v46, 2, v48
	v_lshlrev_b32_e32 v51, 3, v48
	v_and_b32_e32 v46, 12, v46
	v_bfe_u32 v47, v48, 2, 2
	v_lshrrev_b32_e32 v53, 1, v49
	v_lshlrev_b32_e32 v49, 3, v49
	v_xor_b32_e32 v47, v47, v53
	v_and_b32_e32 v184, 8, v49
	v_lshl_add_u64 v[134:135], s[64:65], 0, v[44:45]
	s_mul_i32 s43, s73, 0x300
	s_mul_hi_i32 s42, s73, 0x300
	v_mov_b32_e32 v121, v1
	v_mov_b32_e32 v118, 0
	s_mov_b32 s80, 0
	v_mov_b32_e32 v119, v118
	s_waitcnt vmcnt(11)
	v_fmamk_f32 v18, v18, 0x3a800000, v169
	v_rsq_f32_e32 v18, v18
	v_fmamk_f32 v19, v19, 0x3a800000, v169
	s_waitcnt vmcnt(10)
	v_mul_f32_e32 v167, 0x3a800000, v22
	v_rsq_f32_e32 v19, v19
	v_mul_f32_e32 v22, v167, v167
	v_fmamk_f32 v20, v20, 0x3a800000, v169
	v_fmamk_f32 v21, v21, 0x3a800000, v169
	v_mul_f32_e32 v177, 0x3a800000, v24
	v_fma_f32 v22, v23, s23, -v22
	v_rsq_f32_e32 v20, v20
	v_rsq_f32_e32 v21, v21
	v_mul_f32_e32 v24, v177, v177
	s_waitcnt vmcnt(9)
	v_mul_f32_e32 v178, 0x3a800000, v26
	v_max_f32_e32 v22, 0, v22
	v_mul_f32_e32 v26, v18, v18
	s_waitcnt vmcnt(8)
	v_mul_f32_e32 v179, 0x3a800000, v28
	s_waitcnt vmcnt(7)
; #define LAS __attribute__((address_space(3)))
; __device__ __forceinline__ float row_rs(const float* RSS, int grow) { return __builtin_amdgcn_rsqf(RSS[grow] * (1.0f / 1024.0f) + EPS); }
; __device__ __forceinline__ f32x2 vstat(const float* VS, const float* RSS, int grow) { const float rs = row_rs(RSS, grow); const float mean = VS[2 * grow] * (1.0f / 1024.0f); const float var = fmaxf(VS[2 * grow + 1] * (1.0f / 1024.0f) - mean * mean, 0.f); return (f32x2){mean, rs * __builtin_amdgcn_rsqf(rs * rs * var + EPS)}; }
; __device__ __forceinline__ void mixer_phase(const Args& a, LAS unsigned char* lds, int l, int pass, int tid, int lane, int wave) {
;     ...
;             for (int i = 0; i < 4; ++i) st[i] = vstat(VS, RSS, grow0 + 4 * q + i);
;             float ssb[2] = {0.f, 0.f};
;             v4u vr[4];
; #pragma unroll
;             for (int i = 0; i < 4; ++i) vr[i] = *(const v4u*)(vsrc + (size_t)i * 384);
;             const bf16* wm0 = WM + ((size_t)(l * 8 * 2) * 128 + 32 * wt + fr) * 128 + 8 * fq;
;             const int t0 = 32 * wt + fr, cbw = 64 * wc2 + 8 * fq;
;             const float rsr[2] = {row_rs(RSS, grow0 + t0), row_rs(RSS, grow0 + t0 + 16)};
;             UZ uz[2];
; #pragma unroll
;             for (int m = 0; m < 2; ++m) uz[m] = load_uz_hm(Hu + (size_t)(t0 + 16 * m) * 384, sgb + t0 + 16 * m, cbw);
;     ...
;                     for (int n = 0; n < 4; ++n) { const int R = 64 * wc2 + 16 * n + fr; const int f = (R & 15) ^ ((R >> 5) & 3); Bf[n] = *(const LAS bf16x8*)(VT + R * 256 + (((4 * k + fq) ^ f) << 4)); }
	v_fma_f32 v23, v25, s23, -v24
	v_mul_f32_e32 v24, v178, v178
	v_fmaak_f32 v22, v26, v22, 0x358637bd
	v_mul_f32_e32 v25, v179, v179
	v_max_f32_e32 v23, 0, v23
	v_fma_f32 v24, v27, s23, -v24
	v_mul_f32_e32 v27, v19, v19
	v_rsq_f32_e32 v22, v22
	v_fma_f32 v25, v29, s23, -v25
	v_fmaak_f32 v23, v27, v23, 0x358637bd
	v_max_f32_e32 v24, 0, v24
	v_mul_f32_e32 v28, v20, v20
	v_max_f32_e32 v25, 0, v25
	v_mul_f32_e32 v29, v21, v21
	v_rsq_f32_e32 v23, v23
	v_fmaak_f32 v24, v28, v24, 0x358637bd
	v_fmaak_f32 v25, v29, v25, 0x358637bd
	v_rsq_f32_e32 v24, v24
	v_rsq_f32_e32 v25, v25
	v_mul_f32_e32 v180, v18, v22
	s_waitcnt vmcnt(6)
	v_fmamk_f32 v18, v34, 0x3a800000, v169
	v_rsq_f32_e32 v124, v18
	s_waitcnt vmcnt(5)
	v_fmamk_f32 v18, v35, 0x3a800000, v169
	v_mul_f32_e32 v181, v19, v23
	v_rsq_f32_e32 v126, v18
	v_mad_i64_i32 v[18:19], s[6:7], v43, s31, v[30:31]
	v_lshl_add_u64 v[22:23], v[18:19], 0, v[44:45]
	v_mul_f32_e32 v182, v20, v24
	v_mul_f32_e32 v183, v21, v25
	global_load_dwordx4 v[82:85], v[32:33], off offset:512 nt
	global_load_dwordx4 v[34:37], v[32:33], off offset:64 nt
	global_load_dwordx4 v[38:41], v[32:33], off offset:576 nt
	s_nop 0
	global_load_dwordx4 v[30:33], v[22:23], off nt
	global_load_dwordx4 v[26:29], v[22:23], off offset:512 nt
	global_load_dwordx4 v[18:21], v[22:23], off offset:64 nt
	s_nop 0
	global_load_dwordx4 v[22:25], v[22:23], off offset:576 nt
	s_nop 0
	global_load_dword v127, v[128:129], off
	global_load_dword v205, v[128:129], off offset:64
	s_movk_i32 s6, 0x60
	v_and_or_b32 v49, v51, s6, v46
	v_lshlrev_b32_e32 v185, 8, v49
	v_xor_b32_e32 v49, v47, v46
	v_lshlrev_b32_e32 v186, 4, v49
	v_or_b32_e32 v49, 1, v46
	v_xor_b32_e32 v49, v49, v47
	v_lshlrev_b32_e32 v187, 4, v49
	v_or_b32_e32 v49, 2, v46
	v_or_b32_e32 v46, 3, v46
	v_or_b32_e32 v45, s35, v120
	v_xor_b32_e32 v46, v46, v47
	v_lshlrev_b32_e32 v190, 8, v45
	v_bitop3_b32 v45, v48, s51, 15 bitop3:0x6c
	v_lshlrev_b32_e32 v189, 4, v46
	v_xor_b32_e32 v46, v45, v166
	v_lshlrev_b32_e32 v191, 4, v46
	v_or_b32_e32 v46, s52, v120
	v_lshlrev_b32_e32 v192, 8, v46
	v_bitop3_b32 v46, v48, s53, 15 bitop3:0x6c
	v_xor_b32_e32 v49, v49, v47
	v_xor_b32_e32 v47, v46, v166
	v_lshlrev_b32_e32 v193, 4, v47
	v_or_b32_e32 v47, s59, v120
	v_lshlrev_b32_e32 v194, 8, v47
	v_bitop3_b32 v47, v48, s72, 15 bitop3:0x6c
	v_xor_b32_e32 v48, v47, v166
	v_lshlrev_b32_e32 v195, 4, v48
	v_or_b32_e32 v48, 4, v166
	v_lshlrev_b32_e32 v188, 4, v49
	v_xor_b32_e32 v49, v45, v48
	v_lshlrev_b32_e32 v196, 4, v49
	v_xor_b32_e32 v49, v46, v48
	v_xor_b32_e32 v48, v47, v48
	v_lshlrev_b32_e32 v198, 4, v48
	v_or_b32_e32 v48, 8, v166
	v_lshlrev_b32_e32 v197, 4, v49
	v_xor_b32_e32 v49, v45, v48
	v_lshlrev_b32_e32 v199, 4, v49
	v_xor_b32_e32 v49, v46, v48
	v_xor_b32_e32 v48, v47, v48
	v_lshlrev_b32_e32 v201, 4, v48
	v_or_b32_e32 v48, 12, v166
	v_xor_b32_e32 v45, v45, v48
	s_add_u32 s6, s43, 0x1f400700
	v_lshlrev_b32_e32 v202, 4, v45
	v_xor_b32_e32 v45, v46, v48
	s_addc_u32 s7, s42, 0
	s_add_u32 s6, s6, s100
	s_addc_u32 s7, s7, 0
	v_lshlrev_b32_e32 v203, 4, v45
	v_xor_b32_e32 v45, v47, v48
	v_mov_b64_e32 v[46:47], s[6:7]
	v_mad_i64_i32 v[136:137], s[6:7], v50, s31, v[46:47]
	v_lshl_add_u64 v[46:47], s[26:27], 0, v[120:121]
	v_lshlrev_b64 v[138:139], 8, v[46:47]
	v_add_u32_e32 v46, s75, v120
	s_add_u32 s6, s43, 0x1f400200
	v_ashrrev_i32_e32 v47, 31, v46
	s_addc_u32 s7, s42, 0
	s_add_u32 s6, s6, s100
	s_addc_u32 s7, s7, 0
	v_lshlrev_b64 v[140:141], 8, v[46:47]
	v_mov_b64_e32 v[46:47], s[6:7]
	v_mad_i64_i32 v[144:145], s[6:7], v42, s31, v[46:47]
	v_mad_i64_i32 v[146:147], s[6:7], v43, s31, v[46:47]
	v_lshlrev_b32_e32 v200, 4, v49
	v_lshlrev_b32_e32 v204, 4, v45
	v_or_b32_e32 v136, v136, v0
	v_or_b32_e32 v138, v138, v52
	v_or_b32_e32 v142, v140, v44
	v_mov_b32_e32 v143, v141
	v_or_b32_e32 v144, v144, v44
	v_or_b32_e32 v146, v146, v44
	v_lshl_add_u32 v0, v166, 5, s78
	s_mov_b64 s[42:43], 0
	s_branch .LBB0_176

; #define LAS __attribute__((address_space(3)))
; __device__ __forceinline__ void mixer_phase(const Args& a, LAS unsigned char* lds, int l, int pass, int tid, int lane, int wave) {
;     ...
;             for (int g = 0; g < 8; ++g) {
;                 LAS unsigned char* VT = lds + ((g & 1) ? L_VT1 : L_VT0);
;                 bf16x8 Af[2][4];
; #pragma unroll
;                 for (int m = 0; m < 2; ++m)
; #pragma unroll
;                     for (int k = 0; k < 4; ++k) Af[m][k] = *(const bf16x8*)(wm0 + (size_t)g * 2 * 16384 + (size_t)m * 16 * 128 + 32 * k);
;                 vt_write(VT, vr, st, lng + 128 * g + 8 * o, lnb + 128 * g + 8 * o, q, o);
;                 if (g < 7) {
; #pragma unroll
;                     for (int i = 0; i < 4; ++i) vr[i] = *(const v4u*)(vsrc + (size_t)(g + 1) * HSTR + (size_t)i * 384); }
.LBB0_176:
	v_add_u32_e32 v44, s42, v229
	ds_read_b128 v[78:81], v44 offset:4096
	ds_read_b128 v[86:89], v44
	ds_read_b128 v[90:93], v44 offset:16
	ds_read_b128 v[94:97], v44 offset:4112
	v_lshl_add_u64 v[42:43], s[54:55], 0, v[138:139]
	v_add_co_u32_e32 v44, vcc, s25, v42
	s_mov_b32 s7, 0x401000
	s_nop 0
	v_addc_co_u32_e32 v45, vcc, 0, v43, vcc
	v_add_co_u32_e32 v58, vcc, s7, v42
	s_waitcnt vmcnt(13)
	v_lshlrev_b32_e32 v46, 16, v2
	v_and_b32_e32 v47, 0xffff0000, v2
	v_lshlrev_b32_e32 v48, 16, v3
	v_and_b32_e32 v49, 0xffff0000, v3
	v_lshlrev_b32_e32 v50, 16, v4
	v_and_b32_e32 v51, 0xffff0000, v4
	v_lshlrev_b32_e32 v52, 16, v5
	v_and_b32_e32 v53, 0xffff0000, v5
	s_waitcnt vmcnt(12)
	v_lshlrev_b32_e32 v54, 16, v6
	v_and_b32_e32 v55, 0xffff0000, v6
	v_lshlrev_b32_e32 v56, 16, v7
	v_and_b32_e32 v57, 0xffff0000, v7
	v_lshlrev_b32_e32 v60, 16, v8
	v_and_b32_e32 v61, 0xffff0000, v8
	v_addc_co_u32_e32 v59, vcc, 0, v43, vcc
	v_sub_f32_e32 v100, v46, v167
	v_sub_f32_e32 v101, v47, v167
	v_sub_f32_e32 v102, v48, v167
	v_sub_f32_e32 v103, v49, v167
	v_sub_f32_e32 v104, v50, v167
	v_sub_f32_e32 v105, v51, v167
	v_sub_f32_e32 v106, v52, v167
	v_sub_f32_e32 v107, v53, v167
	v_sub_f32_e32 v108, v54, v177
	v_sub_f32_e32 v109, v55, v177
	v_sub_f32_e32 v110, v56, v177
	v_sub_f32_e32 v111, v57, v177
	v_sub_f32_e32 v112, v60, v177
	v_sub_f32_e32 v113, v61, v177
	global_load_dwordx4 v[62:65], v[44:45], off offset:64
	global_load_dwordx4 v[50:53], v[44:45], off offset:128
	s_nop 0
	global_load_dwordx4 v[42:45], v[44:45], off offset:192
	s_nop 0
	global_load_dwordx4 v[70:73], v[58:59], off offset:-4096
	global_load_dwordx4 v[66:69], v[58:59], off
	global_load_dwordx4 v[54:57], v[58:59], off offset:64
	global_load_dwordx4 v[46:49], v[58:59], off offset:128
	s_nop 0
	global_load_dwordx4 v[58:61], v[58:59], off offset:192
	s_waitcnt vmcnt(19)
	v_lshlrev_b32_e32 v114, 16, v10
	s_waitcnt vmcnt(18)
	v_lshlrev_b32_e32 v150, 16, v14
	v_sub_f32_e32 v114, v114, v178
	v_sub_f32_e32 v150, v150, v179
	v_mul_f32_e32 v100, v180, v100
	v_mul_f32_e32 v108, v181, v108
	v_and_b32_e32 v115, 0xffff0000, v10
	v_mul_f32_e32 v114, v182, v114
	v_and_b32_e32 v151, 0xffff0000, v14
	v_mul_f32_e32 v150, v183, v150
	v_sub_f32_e32 v115, v115, v178
	v_mul_f32_e32 v101, v180, v101
	v_mul_f32_e32 v109, v181, v109
	v_lshlrev_b32_e32 v116, 16, v11
	v_mul_f32_e32 v115, v182, v115
	v_lshlrev_b32_e32 v154, 16, v15
	v_sub_f32_e32 v116, v116, v178
	v_mul_f32_e32 v102, v180, v102
	v_mul_f32_e32 v110, v181, v110
	v_and_b32_e32 v117, 0xffff0000, v11
	v_mul_f32_e32 v116, v182, v116
	v_and_b32_e32 v155, 0xffff0000, v15
	v_sub_f32_e32 v117, v117, v178
	v_mul_f32_e32 v103, v180, v103
	v_mul_f32_e32 v111, v181, v111
	v_mul_f32_e32 v117, v182, v117
	v_lshlrev_b32_e32 v156, 16, v16
	v_and_b32_e32 v157, 0xffff0000, v16
	v_lshlrev_b32_e32 v121, 16, v12
	v_lshlrev_b32_e32 v158, 16, v17
	v_sub_f32_e32 v121, v121, v178
	s_and_b32 s6, s80, 0x8000
	v_and_b32_e32 v99, 0xffff0000, v9
	v_mul_f32_e32 v104, v180, v104
	v_mul_f32_e32 v112, v181, v112
	v_and_b32_e32 v125, 0xffff0000, v12
	v_and_b32_e32 v149, 0xffff0000, v13
	v_mul_f32_e32 v121, v182, v121
	s_waitcnt lgkmcnt(0)
	v_fma_f32 v100, v100, v86, v78
	v_fma_f32 v108, v108, v86, v78
	v_fma_f32 v114, v114, v86, v78
	v_fma_f32 v86, v150, v86, v78
	v_sub_f32_e32 v78, v151, v179
	v_mul_f32_e32 v78, v183, v78
	v_fma_f32 v101, v101, v87, v79
	v_fma_f32 v109, v109, v87, v79
	v_fma_f32 v115, v115, v87, v79
	v_fma_f32 v87, v78, v87, v79
	v_sub_f32_e32 v78, v154, v179
	v_mul_f32_e32 v78, v183, v78
	v_fma_f32 v102, v102, v88, v80
	v_fma_f32 v110, v110, v88, v80
	v_fma_f32 v116, v116, v88, v80
	v_fma_f32 v80, v78, v88, v80
	v_sub_f32_e32 v78, v155, v179
	v_mul_f32_e32 v78, v183, v78
	v_fma_f32 v103, v103, v89, v81
	v_fma_f32 v111, v111, v89, v81
	v_fma_f32 v117, v117, v89, v81
	v_fmac_f32_e32 v81, v78, v89
	v_sub_f32_e32 v78, v156, v179
	v_mul_f32_e32 v78, v183, v78
	v_fma_f32 v88, v78, v90, v94
	v_sub_f32_e32 v78, v157, v179
	v_mul_f32_e32 v78, v183, v78
	v_fma_f32 v89, v78, v91, v95
	v_sub_f32_e32 v78, v158, v179
	v_and_b32_e32 v159, 0xffff0000, v17
	v_mul_f32_e32 v78, v183, v78
	s_add_i32 s6, s6, 0
	v_fma_f32 v104, v104, v90, v94
	v_fma_f32 v112, v112, v90, v94
	v_sub_f32_e32 v99, v99, v177
	v_fma_f32 v121, v121, v90, v94
	v_sub_f32_e32 v125, v125, v178
	v_sub_f32_e32 v149, v149, v178
	v_fma_f32 v90, v78, v92, v96
	v_sub_f32_e32 v78, v159, v179
	v_mul_f32_e32 v105, v180, v105
	v_mul_f32_e32 v107, v180, v107
	v_mul_f32_e32 v113, v181, v113
	v_mul_f32_e32 v99, v181, v99
	v_mul_f32_e32 v125, v182, v125
	v_mul_f32_e32 v149, v182, v149
	v_mul_f32_e32 v78, v183, v78
	v_cvt_pk_bf16_f32 v79, v114, v86
	v_add_u32_e32 v86, s6, v185
	v_fma_f32 v105, v105, v91, v95
	v_fma_f32 v107, v107, v93, v97
	v_fma_f32 v113, v113, v91, v95
	v_fma_f32 v99, v99, v93, v97
	v_fma_f32 v125, v125, v91, v95
	v_fma_f32 v149, v149, v93, v97
	v_fmac_f32_e32 v97, v78, v93
	v_cvt_pk_bf16_f32 v78, v100, v108
	v_add3_u32 v91, v86, v186, v184
	ds_write_b64 v91, v[78:79]
	v_cvt_pk_bf16_f32 v78, v101, v109
	v_cvt_pk_bf16_f32 v79, v115, v87
	v_add3_u32 v87, v86, v187, v184
	ds_write_b64 v87, v[78:79] offset:256
	v_cvt_pk_bf16_f32 v78, v102, v110
	v_cvt_pk_bf16_f32 v79, v116, v80
	v_add3_u32 v80, v86, v188, v184
	v_lshlrev_b32_e32 v98, 16, v9
	v_lshlrev_b32_e32 v148, 16, v13
	ds_write_b64 v80, v[78:79] offset:512
	v_cvt_pk_bf16_f32 v78, v103, v111
	v_cvt_pk_bf16_f32 v79, v117, v81
	v_add3_u32 v81, v86, v189, v184
	v_sub_f32_e32 v98, v98, v177
	v_sub_f32_e32 v148, v148, v178
	ds_write_b64 v81, v[78:79] offset:768
	v_cvt_pk_bf16_f32 v78, v104, v112
	v_cvt_pk_bf16_f32 v79, v121, v88
	v_mul_f32_e32 v106, v180, v106
	v_mul_f32_e32 v98, v181, v98
	v_mul_f32_e32 v148, v182, v148
	ds_write_b64 v91, v[78:79] offset:4096
	v_cvt_pk_bf16_f32 v78, v105, v113
	v_cvt_pk_bf16_f32 v79, v125, v89
	s_cmpk_lg_i32 s42, 0xe00
	v_fma_f32 v106, v106, v92, v96
	v_fma_f32 v98, v98, v92, v96
	v_fma_f32 v148, v148, v92, v96
	ds_write_b64 v87, v[78:79] offset:4352
	v_cvt_pk_bf16_f32 v78, v106, v98
	v_cvt_pk_bf16_f32 v79, v148, v90
	s_cselect_b64 s[44:45], -1, 0
	s_cmpk_eq_i32 s42, 0xe00
	ds_write_b64 v80, v[78:79] offset:4608
	v_cvt_pk_bf16_f32 v78, v107, v99
	v_cvt_pk_bf16_f32 v79, v149, v97
	ds_write_b64 v81, v[78:79] offset:4864
	v_lshl_add_u64 v[14:15], s[54:55], 0, v[136:137]
	global_load_dwordx4 v[2:5], v[14:15], off offset:-1536 nt
	global_load_dwordx4 v[6:9], v[14:15], off offset:-768 nt
	global_load_dwordx4 v[10:13], v[14:15], off nt
	s_nop 0
	global_load_dwordx4 v[14:17], v[14:15], off offset:768 nt
; #define LAS __attribute__((address_space(3)))
; __device__ __forceinline__ void mixer_phase(const Args& a, LAS unsigned char* lds, int l, int pass, int tid, int lane, int wave) {
;     ...
;                 __syncthreads();
;                 pg8::f32x4 acc[2][4];
; #pragma unroll
;                 for (int m = 0; m < 2; ++m)
; #pragma unroll
;                     for (int n = 0; n < 4; ++n) acc[m][n] = (pg8::f32x4){0.f, 0.f, 0.f, 0.f};
; #pragma unroll
;                 for (int k = 0; k < 4; ++k) {
;                     bf16x8 Bf[4];
; #pragma unroll
;                     for (int n = 0; n < 4; ++n) { const int R = 64 * wc2 + 16 * n + fr; const int f = (R & 15) ^ ((R >> 5) & 3); Bf[n] = *(const LAS bf16x8*)(VT + R * 256 + (((4 * k + fq) ^ f) << 4)); }
; #pragma unroll
;                     for (int m = 0; m < 2; ++m)
; #pragma unroll
;                         for (int n = 0; n < 4; ++n) acc[m][n] = __builtin_amdgcn_mfma_f32_16x16x32_bf16(Bf[n], Af[m][k], acc[m][n], 0, 0, 0);
;                 }
;                 UZ nz[2];
; #pragma unroll
;                 for (int m = 0; m < 2; ++m) { nz[m] = uz[m]; if (g < 7) nz[m] = load_uz_hm(Hu + (size_t)(g + 1) * HSTR + (size_t)(t0 + 16 * m) * 384, sgb + (g + 1) * 128 + t0 + 16 * m, cbw); }
; #pragma unroll
;                 for (int m = 0; m < 2; ++m) ssb[m] += sgu_epi(uz[m], acc[m], YMIX + ((size_t)g * MTOT + grow0 + t0 + 16 * m) * 128, 128 * g + cbw, CST + 4096, rsr[m]);
; #pragma unroll
;                 for (int m = 0; m < 2; ++m) uz[m] = nz[m];
.LBB0_178:
	v_add_u32_e32 v121, s6, v190
	v_add_u32_e32 v125, s6, v192
	v_add_u32_e32 v154, s6, v194
	v_add_u32_e32 v86, v121, v191
	v_add_u32_e32 v94, v125, v193
	v_add_u32_e32 v102, v154, v195
	s_waitcnt lgkmcnt(0)
	s_barrier
	ds_read_b128 v[78:81], v86
	ds_read_b128 v[86:89], v86 offset:4096
	ds_read_b128 v[94:97], v94
	ds_read_b128 v[102:105], v102
	v_add_u32_e32 v114, v121, v196
	s_waitcnt vmcnt(4) lgkmcnt(3)
	v_mfma_f32_16x16x32_bf16 v[90:93], v[78:81], v[70:73], 0
	ds_read_b128 v[110:113], v114
	v_add_u32_e32 v148, v154, v198
	ds_read_b128 v[148:151], v148
	s_waitcnt lgkmcnt(4)
	v_mfma_f32_16x16x32_bf16 v[98:101], v[86:89], v[70:73], 0
	s_andn2_b64 vcc, exec, s[44:45]
	s_waitcnt lgkmcnt(3)
	v_mfma_f32_16x16x32_bf16 v[106:109], v[94:97], v[70:73], 0
	s_waitcnt lgkmcnt(2)
	v_mfma_f32_16x16x32_bf16 v[70:73], v[102:105], v[70:73], 0
	s_waitcnt vmcnt(4)
	v_mfma_f32_16x16x32_bf16 v[78:81], v[78:81], v[66:69], 0
	v_mfma_f32_16x16x32_bf16 v[86:89], v[86:89], v[66:69], 0
	v_mfma_f32_16x16x32_bf16 v[94:97], v[94:97], v[66:69], 0
	v_mfma_f32_16x16x32_bf16 v[66:69], v[102:105], v[66:69], 0
	ds_read_b128 v[102:105], v114 offset:4096
	v_add_u32_e32 v114, v125, v197
	ds_read_b128 v[114:117], v114
	s_waitcnt lgkmcnt(3)
	v_mfma_f32_16x16x32_bf16 v[90:93], v[110:113], v[62:65], v[90:93]
	s_waitcnt lgkmcnt(1)
	v_mfma_f32_16x16x32_bf16 v[98:101], v[102:105], v[62:65], v[98:101]
	s_waitcnt lgkmcnt(0)
	v_mfma_f32_16x16x32_bf16 v[106:109], v[114:117], v[62:65], v[106:109]
	v_mfma_f32_16x16x32_bf16 v[62:65], v[148:151], v[62:65], v[70:73]
	s_waitcnt vmcnt(4)
	v_mfma_f32_16x16x32_bf16 v[70:73], v[110:113], v[54:57], v[78:81]
	v_add_u32_e32 v110, v154, v201
	ds_read_b128 v[110:113], v110
	v_mfma_f32_16x16x32_bf16 v[78:81], v[102:105], v[54:57], v[86:89]
	v_add_u32_e32 v102, v121, v199
	v_mfma_f32_16x16x32_bf16 v[86:89], v[114:117], v[54:57], v[94:97]
	s_nop 2
	ds_read_b128 v[94:97], v102
	v_mfma_f32_16x16x32_bf16 v[54:57], v[148:151], v[54:57], v[66:69]
	s_nop 2
	ds_read_b128 v[66:69], v102 offset:4096
	v_add_u32_e32 v102, v125, v200
	ds_read_b128 v[102:105], v102
	s_waitcnt lgkmcnt(2)
	v_mfma_f32_16x16x32_bf16 v[90:93], v[94:97], v[50:53], v[90:93]
	s_waitcnt lgkmcnt(1)
	v_mfma_f32_16x16x32_bf16 v[98:101], v[66:69], v[50:53], v[98:101]
	s_waitcnt lgkmcnt(0)
	v_mfma_f32_16x16x32_bf16 v[106:109], v[102:105], v[50:53], v[106:109]
	v_mfma_f32_16x16x32_bf16 v[50:53], v[110:113], v[50:53], v[62:65]
	s_waitcnt vmcnt(4)
	v_mfma_f32_16x16x32_bf16 v[62:65], v[94:97], v[46:49], v[70:73]
	v_mfma_f32_16x16x32_bf16 v[70:73], v[102:105], v[46:49], v[86:89]
	v_lshl_add_u64 v[102:103], v[128:129], 0, s[42:43]
	s_nop 1
	v_add_u32_e32 v86, v121, v202
	v_mfma_f32_16x16x32_bf16 v[148:151], v[110:113], v[46:49], v[54:57]
	v_mov_b32_e32 v121, v127
	s_nop 1
	v_add_u32_e32 v54, v125, v203
	v_mfma_f32_16x16x32_bf16 v[66:69], v[66:69], v[46:49], v[78:81]
	ds_read_b128 v[46:49], v86 offset:4096
	ds_read_b128 v[54:57], v54
	s_nop 0
	ds_read_b128 v[78:81], v86
	v_add_u32_e32 v86, v154, v204
	ds_read_b128 v[154:157], v86
	s_waitcnt lgkmcnt(1)
	v_mfma_f32_16x16x32_bf16 v[114:117], v[78:81], v[42:45], v[90:93]
	v_mfma_f32_16x16x32_bf16 v[98:101], v[46:49], v[42:45], v[98:101]
	v_mfma_f32_16x16x32_bf16 v[110:113], v[54:57], v[42:45], v[106:109]
	s_waitcnt lgkmcnt(0)
	v_mfma_f32_16x16x32_bf16 v[106:109], v[154:157], v[42:45], v[50:53]
	v_cndmask_b32_e64 v42, 0, 1, s[44:45]
	v_cmp_ne_u32_e64 s[6:7], 1, v42
	v_mov_b64_e32 v[42:43], v[74:75]
	s_waitcnt vmcnt(4)
	v_mfma_f32_16x16x32_bf16 v[94:97], v[78:81], v[58:61], v[62:65]
	v_mov_b64_e32 v[50:51], v[82:83]
	v_mov_b64_e32 v[44:45], v[76:77]
	v_mov_b64_e32 v[52:53], v[84:85]
	v_mfma_f32_16x16x32_bf16 v[90:93], v[46:49], v[58:61], v[66:69]
	v_mov_b64_e32 v[48:49], v[36:37]
	v_mov_b64_e32 v[46:47], v[34:35]
	v_mfma_f32_16x16x32_bf16 v[86:89], v[54:57], v[58:61], v[70:73]
	v_mov_b64_e32 v[56:57], v[40:41]
	v_mov_b64_e32 v[54:55], v[38:39]
	v_mfma_f32_16x16x32_bf16 v[78:81], v[154:157], v[58:61], v[148:151]
	s_cbranch_vccnz .LBB0_180
	v_lshl_add_u64 v[54:55], s[54:55], 0, v[144:145]
	global_load_dwordx4 v[42:45], v[54:55], off offset:-512 nt
	global_load_dwordx4 v[46:49], v[54:55], off offset:-448 nt
	global_load_dwordx4 v[50:53], v[54:55], off nt
	s_nop 0
	global_load_dwordx4 v[54:57], v[54:55], off offset:64 nt
	s_nop 0
	global_load_dword v121, v[102:103], off offset:512
.LBB0_180:
	v_mov_b64_e32 v[60:61], v[32:33]
	v_mov_b64_e32 v[64:65], v[20:21]
	v_mov_b64_e32 v[68:69], v[28:29]
	v_mov_b64_e32 v[72:73], v[24:25]
	s_and_b64 vcc, exec, s[6:7]
	v_mov_b64_e32 v[58:59], v[30:31]
	v_mov_b64_e32 v[62:63], v[18:19]
	v_mov_b64_e32 v[66:67], v[26:27]
	v_mov_b64_e32 v[70:71], v[22:23]
	v_mov_b32_e32 v206, v205
	s_cbranch_vccnz .LBB0_175
	v_lshl_add_u64 v[70:71], s[54:55], 0, v[146:147]
	global_load_dwordx4 v[58:61], v[70:71], off offset:-512 nt
	global_load_dwordx4 v[62:65], v[70:71], off offset:-448 nt
	global_load_dwordx4 v[66:69], v[70:71], off nt
	s_nop 0
	global_load_dwordx4 v[70:73], v[70:71], off offset:64 nt
	s_nop 0
	global_load_dword v206, v[102:103], off offset:576
	s_branch .LBB0_175
